# v084 + RG-LRU gate epilogue rewritten with packed f32 VALU (v_pk_fma/mul/add_f32 on element pairs, same ops and order per element, 4 pairs interleaved)
# speedup vs baseline: 1.0313x; 1.0032x over previous
; #define LAS __attribute__((address_space(3)))
; DI u32x4 pack8f(const float (&f)[8]) { u32x4 r; r[0] = pk2(f[0], f[1]); r[1] = pk2(f[2], f[3]); r[2] = pk2(f[4], f[5]); r[3] = pk2(f[6], f[7]); return r; }
; DI void phase_rglru(const Params& p, unsigned char* shm) {
;     ...
; #pragma unroll
;             for (int j = 0; j < 3; ++j) {
;                 const int q = tid + 512 * j, cc = q % 24;
;                 float a8[8];
;                 { const f32x4 b0 = *(const LAS f32x4*)(cw + 768 + 8 * cc), b1 = *(const LAS f32x4*)(cw + 768 + 8 * cc + 4);
; #pragma unroll
;                   for (int e = 0; e < 4; ++e) { a8[e] = b0[e]; a8[4 + e] = b1[e]; } }
; #pragma unroll
;                 for (int jj = 0; jj < 4; ++jj) {
;                     float xin[8]; { const u32x4 xraw = *(const LAS u32x4*)(lds + XR + jj * TR + loff[j]); unpack8(xraw, xin); }
;                     const f32x4 w0 = *(const LAS f32x4*)(cw + jj * 192 + 8 * cc), w1 = *(const LAS f32x4*)(cw + jj * 192 + 8 * cc + 4);
; #pragma unroll
;                     for (int e = 0; e < 4; ++e) { a8[e] += w0[e] * xin[e]; a8[4 + e] += w1[e] * xin[4 + e]; }
;                 }
;                 *(LAS u32x4*)(lds + XC + loff[j]) = pack8f(a8);
;             }
.LBB0_845:
	s_waitcnt lgkmcnt(0)
	s_barrier
	ds_read_b128 v[120:123], v178
	ds_read_b128 v[124:127], v178 offset:16
	ds_read_b128 v[128:131], v201
	ds_read_b128 v[132:135], v179
	ds_read_b128 v[136:139], v179 offset:16
	ds_read_b128 v[140:143], v201 offset:400
	ds_read_b128 v[144:147], v179 offset:768
	ds_read_b128 v[148:151], v179 offset:784
	ds_read_b128 v[210:213], v201 offset:800
	ds_read_b128 v[214:217], v179 offset:1536
	ds_read_b128 v[218:221], v179 offset:1552
	ds_read_b128 v[222:225], v201 offset:1200
	ds_read_b128 v[226:229], v179 offset:2304
	ds_read_b128 v[230:233], v179 offset:2320
	s_waitcnt lgkmcnt(11)
	v_lshlrev_b32_e32 v170, 16, v128
	v_and_b32_e32 v171, 0xffff0000, v128
	v_lshlrev_b32_e32 v128, 16, v129
	v_and_b32_e32 v129, 0xffff0000, v129
	s_waitcnt lgkmcnt(10)
	v_pk_fma_f32 v[120:121], v[132:133], v[170:171], v[120:121]
	s_waitcnt lgkmcnt(8)
	v_lshlrev_b32_e32 v132, 16, v140
	v_and_b32_e32 v133, 0xffff0000, v140
	v_pk_fma_f32 v[122:123], v[134:135], v[128:129], v[122:123]
	v_lshlrev_b32_e32 v128, 16, v141
	v_and_b32_e32 v129, 0xffff0000, v141
	s_waitcnt lgkmcnt(7)
	v_pk_fma_f32 v[120:121], v[144:145], v[132:133], v[120:121]
	s_waitcnt lgkmcnt(5)
	v_lshlrev_b32_e32 v132, 16, v210
	v_and_b32_e32 v133, 0xffff0000, v210
	v_pk_fma_f32 v[122:123], v[146:147], v[128:129], v[122:123]
	v_lshlrev_b32_e32 v128, 16, v211
	v_and_b32_e32 v129, 0xffff0000, v211
	s_waitcnt lgkmcnt(4)
	v_pk_fma_f32 v[120:121], v[214:215], v[132:133], v[120:121]
	s_waitcnt lgkmcnt(2)
	v_lshlrev_b32_e32 v132, 16, v222
	v_and_b32_e32 v133, 0xffff0000, v222
	v_pk_fma_f32 v[122:123], v[216:217], v[128:129], v[122:123]
	v_lshlrev_b32_e32 v128, 16, v223
	v_and_b32_e32 v129, 0xffff0000, v223
	s_waitcnt lgkmcnt(1)
	v_pk_fma_f32 v[120:121], v[226:227], v[132:133], v[120:121]
	v_lshlrev_b32_e32 v132, 16, v130
	v_and_b32_e32 v133, 0xffff0000, v130
	v_pk_fma_f32 v[122:123], v[228:229], v[128:129], v[122:123]
	v_lshlrev_b32_e32 v128, 16, v131
	v_and_b32_e32 v129, 0xffff0000, v131
	v_pk_fma_f32 v[124:125], v[136:137], v[132:133], v[124:125]
	v_lshlrev_b32_e32 v132, 16, v142
	v_and_b32_e32 v133, 0xffff0000, v142
	v_pk_fma_f32 v[126:127], v[138:139], v[128:129], v[126:127]
	v_lshlrev_b32_e32 v128, 16, v143
	v_and_b32_e32 v129, 0xffff0000, v143
	v_pk_fma_f32 v[124:125], v[148:149], v[132:133], v[124:125]
	v_lshlrev_b32_e32 v132, 16, v212
	v_and_b32_e32 v133, 0xffff0000, v212
	v_pk_fma_f32 v[126:127], v[150:151], v[128:129], v[126:127]
	v_lshlrev_b32_e32 v128, 16, v213
	v_and_b32_e32 v129, 0xffff0000, v213
	v_pk_fma_f32 v[124:125], v[218:219], v[132:133], v[124:125]
	v_lshlrev_b32_e32 v132, 16, v224
	v_and_b32_e32 v133, 0xffff0000, v224
	v_pk_fma_f32 v[126:127], v[220:221], v[128:129], v[126:127]
	v_lshlrev_b32_e32 v128, 16, v225
	v_and_b32_e32 v129, 0xffff0000, v225
	s_waitcnt lgkmcnt(0)
	v_pk_fma_f32 v[124:125], v[230:231], v[132:133], v[124:125]
	v_pk_fma_f32 v[126:127], v[232:233], v[128:129], v[126:127]
	v_cvt_pk_bf16_f32 v120, v120, v121
	v_cvt_pk_bf16_f32 v121, v122, v123
	v_cvt_pk_bf16_f32 v122, v124, v125
	v_cvt_pk_bf16_f32 v123, v126, v127
	ds_write_b128 v201, v[120:123] offset:26880
	ds_read_b128 v[120:123], v180
	ds_read_b128 v[124:127], v180 offset:16
	ds_read_b128 v[128:131], v202
	ds_read_b128 v[132:135], v181
	ds_read_b128 v[136:139], v181 offset:16
	ds_read_b128 v[140:143], v202 offset:400
	ds_read_b128 v[144:147], v181 offset:768
	ds_read_b128 v[148:151], v181 offset:784
	ds_read_b128 v[210:213], v202 offset:800
	ds_read_b128 v[214:217], v181 offset:1536
	ds_read_b128 v[218:221], v181 offset:1552
	ds_read_b128 v[222:225], v202 offset:1200
	ds_read_b128 v[226:229], v181 offset:2304
	ds_read_b128 v[230:233], v181 offset:2320
	s_waitcnt lgkmcnt(11)
	v_lshlrev_b32_e32 v170, 16, v128
	v_and_b32_e32 v171, 0xffff0000, v128
	v_lshlrev_b32_e32 v128, 16, v129
	v_and_b32_e32 v129, 0xffff0000, v129
	s_waitcnt lgkmcnt(10)
	v_pk_fma_f32 v[120:121], v[132:133], v[170:171], v[120:121]
	s_waitcnt lgkmcnt(8)
	v_lshlrev_b32_e32 v132, 16, v140
	v_and_b32_e32 v133, 0xffff0000, v140
	v_pk_fma_f32 v[122:123], v[134:135], v[128:129], v[122:123]
	v_lshlrev_b32_e32 v128, 16, v141
	v_and_b32_e32 v129, 0xffff0000, v141
	s_waitcnt lgkmcnt(7)
	v_pk_fma_f32 v[120:121], v[144:145], v[132:133], v[120:121]
	s_waitcnt lgkmcnt(5)
	v_lshlrev_b32_e32 v132, 16, v210
	v_and_b32_e32 v133, 0xffff0000, v210
	v_pk_fma_f32 v[122:123], v[146:147], v[128:129], v[122:123]
	v_lshlrev_b32_e32 v128, 16, v211
	v_and_b32_e32 v129, 0xffff0000, v211
	s_waitcnt lgkmcnt(4)
	v_pk_fma_f32 v[120:121], v[214:215], v[132:133], v[120:121]
	s_waitcnt lgkmcnt(2)
	v_lshlrev_b32_e32 v132, 16, v222
	v_and_b32_e32 v133, 0xffff0000, v222
	v_pk_fma_f32 v[122:123], v[216:217], v[128:129], v[122:123]
	v_lshlrev_b32_e32 v128, 16, v223
	v_and_b32_e32 v129, 0xffff0000, v223
	s_waitcnt lgkmcnt(1)
	v_pk_fma_f32 v[120:121], v[226:227], v[132:133], v[120:121]
	v_lshlrev_b32_e32 v132, 16, v130
	v_and_b32_e32 v133, 0xffff0000, v130
	v_pk_fma_f32 v[122:123], v[228:229], v[128:129], v[122:123]
	v_lshlrev_b32_e32 v128, 16, v131
	v_and_b32_e32 v129, 0xffff0000, v131
	v_pk_fma_f32 v[124:125], v[136:137], v[132:133], v[124:125]
	v_lshlrev_b32_e32 v132, 16, v142
	v_and_b32_e32 v133, 0xffff0000, v142
	v_pk_fma_f32 v[126:127], v[138:139], v[128:129], v[126:127]
	v_lshlrev_b32_e32 v128, 16, v143
	v_and_b32_e32 v129, 0xffff0000, v143
	v_pk_fma_f32 v[124:125], v[148:149], v[132:133], v[124:125]
	v_lshlrev_b32_e32 v132, 16, v212
	v_and_b32_e32 v133, 0xffff0000, v212
	v_pk_fma_f32 v[126:127], v[150:151], v[128:129], v[126:127]
	v_lshlrev_b32_e32 v128, 16, v213
	v_and_b32_e32 v129, 0xffff0000, v213
	v_pk_fma_f32 v[124:125], v[218:219], v[132:133], v[124:125]
	v_lshlrev_b32_e32 v132, 16, v224
	v_and_b32_e32 v133, 0xffff0000, v224
	v_pk_fma_f32 v[126:127], v[220:221], v[128:129], v[126:127]
	v_lshlrev_b32_e32 v128, 16, v225
	v_and_b32_e32 v129, 0xffff0000, v225
	s_waitcnt lgkmcnt(0)
; #define LAS __attribute__((address_space(3)))
; DI u32x4 pack8f(const float (&f)[8]) { u32x4 r; r[0] = pk2(f[0], f[1]); r[1] = pk2(f[2], f[3]); r[2] = pk2(f[4], f[5]); r[3] = pk2(f[6], f[7]); return r; }
; DI void phase_rglru(const Params& p, unsigned char* shm) {
;     ...
; #pragma unroll
;             for (int j = 0; j < 3; ++j) {
;                 const int q = tid + 512 * j, cc = q % 24;
;                 float a8[8];
;                 { const f32x4 b0 = *(const LAS f32x4*)(cw + 768 + 8 * cc), b1 = *(const LAS f32x4*)(cw + 768 + 8 * cc + 4);
; #pragma unroll
;                   for (int e = 0; e < 4; ++e) { a8[e] = b0[e]; a8[4 + e] = b1[e]; } }
; #pragma unroll
;                 for (int jj = 0; jj < 4; ++jj) {
;                     float xin[8]; { const u32x4 xraw = *(const LAS u32x4*)(lds + XR + jj * TR + loff[j]); unpack8(xraw, xin); }
;                     const f32x4 w0 = *(const LAS f32x4*)(cw + jj * 192 + 8 * cc), w1 = *(const LAS f32x4*)(cw + jj * 192 + 8 * cc + 4);
; #pragma unroll
;                     for (int e = 0; e < 4; ++e) { a8[e] += w0[e] * xin[e]; a8[4 + e] += w1[e] * xin[4 + e]; }
;                 }
;                 *(LAS u32x4*)(lds + XC + loff[j]) = pack8f(a8);
;             }
;             __syncthreads();
;             {
; #pragma unroll
;                 for (int u = 0; u < 2; ++u) {
;                     if (u == 1 && w >= 4) break;
;                     f32x4 acc[4][2];
; #pragma unroll
;                     for (int mt = 0; mt < 4; ++mt) { acc[mt][0] = (f32x4){0.f, 0.f, 0.f, 0.f}; acc[mt][1] = (f32x4){0.f, 0.f, 0.f, 0.f}; }
; #pragma unroll
;                     for (int kk = 0; kk < 6; ++kk)
; #pragma unroll
;                         for (int mt = 0; mt < 4; ++mt) {
;                             const bf16x8 af = *(const LAS bf16x8*)(lds + XC + (16 * mt + fr) * TR + (32 * kk + 8 * fq) * 2);
;                             acc[mt][0] = __builtin_amdgcn_mfma_f32_16x16x32_bf16(af, Bf[u][kk], acc[mt][0], 0, 0, 0);
;                             acc[mt][1] = __builtin_amdgcn_mfma_f32_16x16x32_bf16(af, Bf[2 + u][kk], acc[mt][1], 0, 0, 0);
;                         }
	v_pk_fma_f32 v[124:125], v[230:231], v[132:133], v[124:125]
	v_pk_fma_f32 v[126:127], v[232:233], v[128:129], v[126:127]
	v_cvt_pk_bf16_f32 v120, v120, v121
	v_cvt_pk_bf16_f32 v121, v122, v123
	v_cvt_pk_bf16_f32 v122, v124, v125
	v_cvt_pk_bf16_f32 v123, v126, v127
	ds_write_b128 v202, v[120:123] offset:26880
	ds_read_b128 v[120:123], v182
	ds_read_b128 v[124:127], v182 offset:16
	ds_read_b128 v[128:131], v203
	ds_read_b128 v[132:135], v183
	ds_read_b128 v[136:139], v183 offset:16
	ds_read_b128 v[140:143], v203 offset:400
	ds_read_b128 v[144:147], v183 offset:768
	ds_read_b128 v[148:151], v183 offset:784
	ds_read_b128 v[210:213], v203 offset:800
	ds_read_b128 v[214:217], v183 offset:1536
	ds_read_b128 v[218:221], v183 offset:1552
	ds_read_b128 v[222:225], v203 offset:1200
	ds_read_b128 v[226:229], v183 offset:2304
	ds_read_b128 v[230:233], v183 offset:2320
	s_waitcnt lgkmcnt(11)
	v_lshlrev_b32_e32 v170, 16, v128
	v_and_b32_e32 v171, 0xffff0000, v128
	v_lshlrev_b32_e32 v128, 16, v129
	v_and_b32_e32 v129, 0xffff0000, v129
	s_waitcnt lgkmcnt(10)
	v_pk_fma_f32 v[120:121], v[132:133], v[170:171], v[120:121]
	s_waitcnt lgkmcnt(8)
	v_lshlrev_b32_e32 v132, 16, v140
	v_and_b32_e32 v133, 0xffff0000, v140
	v_pk_fma_f32 v[122:123], v[134:135], v[128:129], v[122:123]
	v_lshlrev_b32_e32 v128, 16, v141
	v_and_b32_e32 v129, 0xffff0000, v141
	s_waitcnt lgkmcnt(7)
	v_pk_fma_f32 v[120:121], v[144:145], v[132:133], v[120:121]
	s_waitcnt lgkmcnt(5)
	v_lshlrev_b32_e32 v132, 16, v210
	v_and_b32_e32 v133, 0xffff0000, v210
	v_pk_fma_f32 v[122:123], v[146:147], v[128:129], v[122:123]
	v_lshlrev_b32_e32 v128, 16, v211
	v_and_b32_e32 v129, 0xffff0000, v211
	s_waitcnt lgkmcnt(4)
	v_pk_fma_f32 v[120:121], v[214:215], v[132:133], v[120:121]
	s_waitcnt lgkmcnt(2)
	v_lshlrev_b32_e32 v132, 16, v222
	v_and_b32_e32 v133, 0xffff0000, v222
	v_pk_fma_f32 v[122:123], v[216:217], v[128:129], v[122:123]
	v_lshlrev_b32_e32 v128, 16, v223
	v_and_b32_e32 v129, 0xffff0000, v223
	s_waitcnt lgkmcnt(1)
	v_pk_fma_f32 v[120:121], v[226:227], v[132:133], v[120:121]
	v_lshlrev_b32_e32 v132, 16, v130
	v_and_b32_e32 v133, 0xffff0000, v130
	v_pk_fma_f32 v[122:123], v[228:229], v[128:129], v[122:123]
	v_lshlrev_b32_e32 v128, 16, v131
	v_and_b32_e32 v129, 0xffff0000, v131
	v_pk_fma_f32 v[124:125], v[136:137], v[132:133], v[124:125]
	v_lshlrev_b32_e32 v132, 16, v142
	v_and_b32_e32 v133, 0xffff0000, v142
	v_pk_fma_f32 v[126:127], v[138:139], v[128:129], v[126:127]
	v_lshlrev_b32_e32 v128, 16, v143
	v_and_b32_e32 v129, 0xffff0000, v143
	v_pk_fma_f32 v[124:125], v[148:149], v[132:133], v[124:125]
	v_lshlrev_b32_e32 v132, 16, v212
	v_and_b32_e32 v133, 0xffff0000, v212
	v_pk_fma_f32 v[126:127], v[150:151], v[128:129], v[126:127]
	v_lshlrev_b32_e32 v128, 16, v213
	v_and_b32_e32 v129, 0xffff0000, v213
	v_pk_fma_f32 v[124:125], v[218:219], v[132:133], v[124:125]
	v_lshlrev_b32_e32 v132, 16, v224
	v_and_b32_e32 v133, 0xffff0000, v224
	v_pk_fma_f32 v[126:127], v[220:221], v[128:129], v[126:127]
	v_lshlrev_b32_e32 v128, 16, v225
	v_and_b32_e32 v129, 0xffff0000, v225
	s_waitcnt lgkmcnt(0)
	v_pk_fma_f32 v[124:125], v[230:231], v[132:133], v[124:125]
	v_pk_fma_f32 v[126:127], v[232:233], v[128:129], v[126:127]
	v_cvt_pk_bf16_f32 v120, v120, v121
	v_cvt_pk_bf16_f32 v121, v122, v123
	v_cvt_pk_bf16_f32 v122, v124, v125
	v_cvt_pk_bf16_f32 v123, v126, v127
	ds_write_b128 v203, v[120:123] offset:26880
	s_waitcnt lgkmcnt(0)
	s_barrier
	ds_read_b128 v[120:123], v204 offset:26880
	ds_read_b128 v[124:127], v204 offset:33280
	ds_read_b128 v[128:131], v204 offset:39680
	ds_read_b128 v[132:135], v204 offset:46080
	ds_read_b128 v[226:229], v204 offset:26944
	s_waitcnt lgkmcnt(4)
	v_mfma_f32_16x16x32_bf16 v[148:151], v[120:123], v[0:3], 0
	v_mfma_f32_16x16x32_bf16 v[144:147], v[120:123], v[48:51], 0
	ds_read_b128 v[230:233], v204 offset:33344
	s_waitcnt lgkmcnt(4)
	v_mfma_f32_16x16x32_bf16 v[140:143], v[124:127], v[0:3], 0
	v_mfma_f32_16x16x32_bf16 v[136:139], v[124:127], v[48:51], 0
	ds_read_b128 v[120:123], v204 offset:39744
	s_waitcnt lgkmcnt(4)
	v_mfma_f32_16x16x32_bf16 v[214:217], v[128:131], v[0:3], 0
	v_mfma_f32_16x16x32_bf16 v[210:213], v[128:131], v[48:51], 0
	ds_read_b128 v[124:127], v204 offset:46144
	s_waitcnt lgkmcnt(4)
	v_mfma_f32_16x16x32_bf16 v[218:221], v[132:135], v[0:3], 0
	v_mfma_f32_16x16x32_bf16 v[222:225], v[132:135], v[48:51], 0
	ds_read_b128 v[128:131], v204 offset:27008
	s_waitcnt lgkmcnt(4)
	v_mfma_f32_16x16x32_bf16 v[148:151], v[226:229], v[4:7], v[148:151]
	v_mfma_f32_16x16x32_bf16 v[144:147], v[226:229], v[52:55], v[144:147]
	ds_read_b128 v[132:135], v204 offset:33408
	s_waitcnt lgkmcnt(4)
	v_mfma_f32_16x16x32_bf16 v[140:143], v[230:233], v[4:7], v[140:143]
	v_mfma_f32_16x16x32_bf16 v[136:139], v[230:233], v[52:55], v[136:139]
	ds_read_b128 v[226:229], v204 offset:39808
	s_waitcnt lgkmcnt(4)
	v_mfma_f32_16x16x32_bf16 v[214:217], v[120:123], v[4:7], v[214:217]
	v_mfma_f32_16x16x32_bf16 v[210:213], v[120:123], v[52:55], v[210:213]
	ds_read_b128 v[230:233], v204 offset:46208
	s_waitcnt lgkmcnt(4)
	v_mfma_f32_16x16x32_bf16 v[218:221], v[124:127], v[4:7], v[218:221]
	v_mfma_f32_16x16x32_bf16 v[222:225], v[124:127], v[52:55], v[222:225]
	ds_read_b128 v[120:123], v204 offset:27072
	s_waitcnt lgkmcnt(4)
	v_mfma_f32_16x16x32_bf16 v[148:151], v[128:131], v[8:11], v[148:151]
	v_mfma_f32_16x16x32_bf16 v[144:147], v[128:131], v[56:59], v[144:147]
	ds_read_b128 v[124:127], v204 offset:33472
	s_waitcnt lgkmcnt(4)
	v_mfma_f32_16x16x32_bf16 v[140:143], v[132:135], v[8:11], v[140:143]
	v_mfma_f32_16x16x32_bf16 v[136:139], v[132:135], v[56:59], v[136:139]
	ds_read_b128 v[128:131], v204 offset:39872
	s_waitcnt lgkmcnt(4)
; #define LAS __attribute__((address_space(3)))
; DI void phase_rglru(const Params& p, unsigned char* shm) {
;     ...
;                     for (int kk = 0; kk < 6; ++kk)
; #pragma unroll
;                         for (int mt = 0; mt < 4; ++mt) {
;                             const bf16x8 af = *(const LAS bf16x8*)(lds + XC + (16 * mt + fr) * TR + (32 * kk + 8 * fq) * 2);
;                             acc[mt][0] = __builtin_amdgcn_mfma_f32_16x16x32_bf16(af, Bf[u][kk], acc[mt][0], 0, 0, 0);
;                             acc[mt][1] = __builtin_amdgcn_mfma_f32_16x16x32_bf16(af, Bf[2 + u][kk], acc[mt][1], 0, 0, 0);
;                         }
;                     const int ch = chb + 16 * u + fr;
;                     const float ba = gb[ch], bx = gb[192 + ch], sp = gb[384 + ch];
; #pragma unroll
;                     for (int mt = 0; mt < 4; ++mt)
; #pragma unroll
;                         for (int j = 0; j < 4; ++j) {
;                             const int t = 16 * mt + 4 * fq + j;
;                             const float ea = 1.f + __expf(fminf(-(acc[mt][0][j] + ba), 40.f)), ex = 1.f + __expf(fminf(-(acc[mt][1][j] + bx), 40.f));
;                             const float inv = __builtin_amdgcn_rcpf(ea * ex);
;                             const float r = inv * ex, ig = inv * ea;
;                             const float av = __expf(r * sp), om = 1.f - av;
;                             const float xcv = __uint_as_float((unsigned)*(const LAS bf16_t*)(lds + XC + t * TR + ch * 2) << 16);
;                             const float bt = __builtin_amdgcn_sqrtf(fmaxf(om * (1.f + av), 0.f)) * (ig * xcv);
	v_mfma_f32_16x16x32_bf16 v[214:217], v[226:229], v[8:11], v[214:217]
	v_mfma_f32_16x16x32_bf16 v[210:213], v[226:229], v[56:59], v[210:213]
	ds_read_b128 v[132:135], v204 offset:46272
	s_waitcnt lgkmcnt(4)
	v_mfma_f32_16x16x32_bf16 v[218:221], v[230:233], v[8:11], v[218:221]
	v_mfma_f32_16x16x32_bf16 v[222:225], v[230:233], v[56:59], v[222:225]
	ds_read_b128 v[226:229], v204 offset:27136
	s_waitcnt lgkmcnt(4)
	v_mfma_f32_16x16x32_bf16 v[148:151], v[120:123], v[12:15], v[148:151]
	v_mfma_f32_16x16x32_bf16 v[144:147], v[120:123], v[60:63], v[144:147]
	ds_read_b128 v[230:233], v204 offset:33536
	s_waitcnt lgkmcnt(4)
	v_mfma_f32_16x16x32_bf16 v[140:143], v[124:127], v[12:15], v[140:143]
	v_mfma_f32_16x16x32_bf16 v[136:139], v[124:127], v[60:63], v[136:139]
	ds_read_b128 v[120:123], v204 offset:39936
	s_waitcnt lgkmcnt(4)
	v_mfma_f32_16x16x32_bf16 v[214:217], v[128:131], v[12:15], v[214:217]
	v_mfma_f32_16x16x32_bf16 v[210:213], v[128:131], v[60:63], v[210:213]
	ds_read_b128 v[124:127], v204 offset:46336
	s_waitcnt lgkmcnt(4)
	v_mfma_f32_16x16x32_bf16 v[218:221], v[132:135], v[12:15], v[218:221]
	v_mfma_f32_16x16x32_bf16 v[222:225], v[132:135], v[60:63], v[222:225]
	ds_read_b128 v[128:131], v204 offset:27200
	s_waitcnt lgkmcnt(4)
	v_mfma_f32_16x16x32_bf16 v[148:151], v[226:229], v[16:19], v[148:151]
	v_mfma_f32_16x16x32_bf16 v[144:147], v[226:229], v[64:67], v[144:147]
	ds_read_b128 v[132:135], v204 offset:33600
	s_waitcnt lgkmcnt(4)
	v_mfma_f32_16x16x32_bf16 v[140:143], v[230:233], v[16:19], v[140:143]
	v_mfma_f32_16x16x32_bf16 v[136:139], v[230:233], v[64:67], v[136:139]
	s_waitcnt lgkmcnt(3)
	v_mfma_f32_16x16x32_bf16 v[214:217], v[120:123], v[16:19], v[214:217]
	v_mfma_f32_16x16x32_bf16 v[210:213], v[120:123], v[64:67], v[210:213]
	s_waitcnt lgkmcnt(2)
	v_mfma_f32_16x16x32_bf16 v[218:221], v[124:127], v[16:19], v[218:221]
	v_mfma_f32_16x16x32_bf16 v[222:225], v[124:127], v[64:67], v[222:225]
	s_waitcnt lgkmcnt(1)
	v_mfma_f32_16x16x32_bf16 v[148:151], v[128:131], v[20:23], v[148:151]
	v_mfma_f32_16x16x32_bf16 v[144:147], v[128:131], v[68:71], v[144:147]
	s_waitcnt lgkmcnt(0)
	v_mfma_f32_16x16x32_bf16 v[140:143], v[132:135], v[20:23], v[140:143]
	v_mfma_f32_16x16x32_bf16 v[136:139], v[132:135], v[68:71], v[136:139]
	ds_read_b128 v[120:123], v204 offset:40000
	s_nop 1
	ds_read_b128 v[128:131], v204 offset:46400
	ds_read2st64_b32 v[170:171], v184 offset1:3
	ds_read_b32 v205, v184 offset:1536
	ds_read_u16 v226, v194 offset:26880
	ds_read_u16 v227, v194 offset:27280
	ds_read_u16 v228, v194 offset:27680
	ds_read_u16 v229, v194 offset:28080
	ds_read_u16 v230, v194 offset:33280
	ds_read_u16 v231, v194 offset:33680
	ds_read_u16 v232, v194 offset:34080
	ds_read_u16 v233, v194 offset:34480
	ds_read_u16 v234, v194 offset:39680
	ds_read_u16 v235, v194 offset:40080
	ds_read_u16 v236, v194 offset:40480
	ds_read_u16 v237, v194 offset:40880
	ds_read_u16 v238, v194 offset:46080
	ds_read_u16 v239, v194 offset:46480
	ds_read_u16 v240, v194 offset:46880
	ds_read_u16 v241, v194 offset:47280
	s_waitcnt lgkmcnt(15)
	v_mov_b32_e32 v242, 0xbfb8aa3b
	v_mov_b32_e32 v243, 0x4266d4ca
	v_mul_f32_e32 v170, v242, v170
	v_mul_f32_e32 v171, v242, v171
	v_mul_f32_e32 v205, 0x3fb8aa3b, v205
	v_mfma_f32_16x16x32_bf16 v[124:127], v[120:123], v[20:23], v[214:217]
	v_mfma_f32_16x16x32_bf16 v[120:123], v[120:123], v[68:71], v[210:213]
	v_mfma_f32_16x16x32_bf16 v[132:135], v[128:131], v[20:23], v[218:221]
	v_mfma_f32_16x16x32_bf16 v[128:131], v[128:131], v[68:71], v[222:225]
	v_pk_fma_f32 v[148:149], v[148:149], v[242:243], v[170:171] op_sel_hi:[1,0,0]
	v_pk_fma_f32 v[144:145], v[144:145], v[242:243], v[170:171] op_sel:[0,0,1] op_sel_hi:[1,0,1]
	v_pk_fma_f32 v[150:151], v[150:151], v[242:243], v[170:171] op_sel_hi:[1,0,0]
	v_pk_fma_f32 v[146:147], v[146:147], v[242:243], v[170:171] op_sel:[0,0,1] op_sel_hi:[1,0,1]
	v_pk_fma_f32 v[140:141], v[140:141], v[242:243], v[170:171] op_sel_hi:[1,0,0]
	v_pk_fma_f32 v[136:137], v[136:137], v[242:243], v[170:171] op_sel:[0,0,1] op_sel_hi:[1,0,1]
	v_pk_fma_f32 v[142:143], v[142:143], v[242:243], v[170:171] op_sel_hi:[1,0,0]
	v_pk_fma_f32 v[138:139], v[138:139], v[242:243], v[170:171] op_sel:[0,0,1] op_sel_hi:[1,0,1]
	v_min_f32_e32 v148, v243, v148
	v_min_f32_e32 v149, v243, v149
	v_min_f32_e32 v144, v243, v144
	v_min_f32_e32 v145, v243, v145
	v_min_f32_e32 v150, v243, v150
	v_min_f32_e32 v151, v243, v151
	v_min_f32_e32 v146, v243, v146
	v_min_f32_e32 v147, v243, v147
	v_min_f32_e32 v140, v243, v140
	v_min_f32_e32 v141, v243, v141
	v_min_f32_e32 v136, v243, v136
	v_min_f32_e32 v137, v243, v137
	v_min_f32_e32 v142, v243, v142
	v_min_f32_e32 v143, v243, v143
	v_min_f32_e32 v138, v243, v138
	v_min_f32_e32 v139, v243, v139
	v_exp_f32_e32 v148, v148
	v_exp_f32_e32 v149, v149
	v_exp_f32_e32 v144, v144
	v_exp_f32_e32 v145, v145
	v_exp_f32_e32 v150, v150
	v_exp_f32_e32 v151, v151
	v_exp_f32_e32 v146, v146
	v_exp_f32_e32 v147, v147
	v_exp_f32_e32 v140, v140
	v_exp_f32_e32 v141, v141
	v_exp_f32_e32 v136, v136
	v_exp_f32_e32 v137, v137
	v_exp_f32_e32 v142, v142
	v_exp_f32_e32 v143, v143
	v_exp_f32_e32 v138, v138
	v_exp_f32_e32 v139, v139
	v_pk_add_f32 v[148:149], v[148:149], 1.0 op_sel_hi:[1,0]
	v_pk_add_f32 v[144:145], v[144:145], 1.0 op_sel_hi:[1,0]
	v_pk_add_f32 v[150:151], v[150:151], 1.0 op_sel_hi:[1,0]
	v_pk_add_f32 v[146:147], v[146:147], 1.0 op_sel_hi:[1,0]
	v_pk_add_f32 v[140:141], v[140:141], 1.0 op_sel_hi:[1,0]
	v_pk_add_f32 v[136:137], v[136:137], 1.0 op_sel_hi:[1,0]
	v_pk_add_f32 v[142:143], v[142:143], 1.0 op_sel_hi:[1,0]
	v_pk_add_f32 v[138:139], v[138:139], 1.0 op_sel_hi:[1,0]
	v_pk_mul_f32 v[210:211], v[148:149], v[144:145]
; #define LAS __attribute__((address_space(3)))
; DI unsigned pk2(float a, float b) { f32x2 v = {a, b}; bf2_t r = __builtin_convertvector(v, bf2_t); return __builtin_bit_cast(unsigned, r); }
; DI void phase_rglru(const Params& p, unsigned char* shm) {
;     ...
;                             const float ea = 1.f + __expf(fminf(-(acc[mt][0][j] + ba), 40.f)), ex = 1.f + __expf(fminf(-(acc[mt][1][j] + bx), 40.f));
;                             const float inv = __builtin_amdgcn_rcpf(ea * ex);
;                             const float r = inv * ex, ig = inv * ea;
;                             const float av = __expf(r * sp), om = 1.f - av;
;                             const float xcv = __uint_as_float((unsigned)*(const LAS bf16_t*)(lds + XC + t * TR + ch * 2) << 16);
;                             const float bt = __builtin_amdgcn_sqrtf(fmaxf(om * (1.f + av), 0.f)) * (ig * xcv);
;                             *(LAS bf16_t*)(lds + LAo + t * TR + ch * 2) = (bf16_t)(pk2(om, 0.f) & 0xffffu);
;                             *(LAS bf16_t*)(lds + BTo + t * TR + ch * 2) = (bf16_t)(pk2(bt, 0.f) & 0xffffu);
	v_pk_mul_f32 v[212:213], v[150:151], v[146:147]
	v_pk_mul_f32 v[214:215], v[140:141], v[136:137]
	v_pk_mul_f32 v[216:217], v[142:143], v[138:139]
	v_rcp_f32_e32 v210, v210
	v_rcp_f32_e32 v211, v211
	v_rcp_f32_e32 v212, v212
	v_rcp_f32_e32 v213, v213
	v_rcp_f32_e32 v214, v214
	v_rcp_f32_e32 v215, v215
	v_rcp_f32_e32 v216, v216
	v_rcp_f32_e32 v217, v217
	v_pk_mul_f32 v[144:145], v[144:145], v[210:211]
	v_pk_mul_f32 v[148:149], v[148:149], v[210:211]
	v_pk_mul_f32 v[146:147], v[146:147], v[212:213]
	v_pk_mul_f32 v[150:151], v[150:151], v[212:213]
	v_pk_mul_f32 v[136:137], v[136:137], v[214:215]
	v_pk_mul_f32 v[140:141], v[140:141], v[214:215]
	v_pk_mul_f32 v[138:139], v[138:139], v[216:217]
	v_pk_mul_f32 v[142:143], v[142:143], v[216:217]
	v_pk_mul_f32 v[144:145], v[144:145], v[204:205] op_sel:[0,1] op_sel_hi:[1,1]
	v_pk_mul_f32 v[146:147], v[146:147], v[204:205] op_sel:[0,1] op_sel_hi:[1,1]
	v_pk_mul_f32 v[136:137], v[136:137], v[204:205] op_sel:[0,1] op_sel_hi:[1,1]
	v_pk_mul_f32 v[138:139], v[138:139], v[204:205] op_sel:[0,1] op_sel_hi:[1,1]
	v_exp_f32_e32 v144, v144
	v_exp_f32_e32 v145, v145
	v_exp_f32_e32 v146, v146
	v_exp_f32_e32 v147, v147
	v_exp_f32_e32 v136, v136
	v_exp_f32_e32 v137, v137
	v_exp_f32_e32 v138, v138
	v_exp_f32_e32 v139, v139
	v_pk_add_f32 v[210:211], v[144:145], 1.0 op_sel_hi:[1,0] neg_lo:[1,0] neg_hi:[1,0]
	v_pk_add_f32 v[144:145], v[144:145], 1.0 op_sel_hi:[1,0]
	v_pk_add_f32 v[212:213], v[146:147], 1.0 op_sel_hi:[1,0] neg_lo:[1,0] neg_hi:[1,0]
	v_pk_add_f32 v[146:147], v[146:147], 1.0 op_sel_hi:[1,0]
	v_pk_add_f32 v[214:215], v[136:137], 1.0 op_sel_hi:[1,0] neg_lo:[1,0] neg_hi:[1,0]
	v_pk_add_f32 v[136:137], v[136:137], 1.0 op_sel_hi:[1,0]
	v_pk_add_f32 v[216:217], v[138:139], 1.0 op_sel_hi:[1,0] neg_lo:[1,0] neg_hi:[1,0]
	v_pk_add_f32 v[138:139], v[138:139], 1.0 op_sel_hi:[1,0]
	v_pk_mul_f32 v[144:145], v[210:211], v[144:145]
	v_pk_mul_f32 v[146:147], v[212:213], v[146:147]
	v_pk_mul_f32 v[136:137], v[214:215], v[136:137]
	v_pk_mul_f32 v[138:139], v[216:217], v[138:139]
	v_max_f32_e32 v144, 0, v144
	v_max_f32_e32 v145, 0, v145
	v_max_f32_e32 v146, 0, v146
	v_max_f32_e32 v147, 0, v147
	v_max_f32_e32 v136, 0, v136
	v_max_f32_e32 v137, 0, v137
	v_max_f32_e32 v138, 0, v138
	v_max_f32_e32 v139, 0, v139
	v_sqrt_f32_e32 v144, v144
	v_sqrt_f32_e32 v145, v145
	v_sqrt_f32_e32 v146, v146
	v_sqrt_f32_e32 v147, v147
	v_sqrt_f32_e32 v136, v136
	v_sqrt_f32_e32 v137, v137
	v_sqrt_f32_e32 v138, v138
	v_sqrt_f32_e32 v139, v139
	s_waitcnt lgkmcnt(0)
	v_lshlrev_b32_e32 v226, 16, v226
	v_lshlrev_b32_e32 v227, 16, v227
	v_lshlrev_b32_e32 v228, 16, v228
	v_lshlrev_b32_e32 v229, 16, v229
	v_lshlrev_b32_e32 v230, 16, v230
	v_lshlrev_b32_e32 v231, 16, v231
	v_lshlrev_b32_e32 v232, 16, v232
	v_lshlrev_b32_e32 v233, 16, v233
	v_pk_mul_f32 v[148:149], v[148:149], v[226:227]
	v_pk_mul_f32 v[150:151], v[150:151], v[228:229]
	v_pk_mul_f32 v[140:141], v[140:141], v[230:231]
	v_pk_mul_f32 v[142:143], v[142:143], v[232:233]
	v_pk_mul_f32 v[148:149], v[148:149], v[144:145]
	v_pk_mul_f32 v[150:151], v[150:151], v[146:147]
	v_pk_mul_f32 v[140:141], v[140:141], v[136:137]
	v_pk_mul_f32 v[142:143], v[142:143], v[138:139]
	v_cvt_pk_bf16_f32 v210, v210, v211
	v_cvt_pk_bf16_f32 v148, v148, v149
	v_cvt_pk_bf16_f32 v212, v212, v213
	v_cvt_pk_bf16_f32 v150, v150, v151
	v_cvt_pk_bf16_f32 v214, v214, v215
	v_cvt_pk_bf16_f32 v140, v140, v141
	v_cvt_pk_bf16_f32 v216, v216, v217
	v_cvt_pk_bf16_f32 v142, v142, v143
	ds_write_b16 v195, v210
	ds_write_b16_d16_hi v195, v210 offset:400
	ds_write_b16 v196, v148
	ds_write_b16_d16_hi v196, v148 offset:400
	ds_write_b16 v195, v212 offset:800
	ds_write_b16_d16_hi v195, v212 offset:1200
	ds_write_b16 v196, v150 offset:800
	ds_write_b16_d16_hi v196, v150 offset:1200
	ds_write_b16 v195, v214 offset:6400
	ds_write_b16_d16_hi v195, v214 offset:6800
	ds_write_b16 v196, v140 offset:6400
	ds_write_b16_d16_hi v196, v140 offset:6800
	ds_write_b16 v195, v216 offset:7200
	ds_write_b16_d16_hi v195, v216 offset:7600
	ds_write_b16 v196, v142 offset:7200
	ds_write_b16_d16_hi v196, v142 offset:7600
	v_pk_fma_f32 v[124:125], v[124:125], v[242:243], v[170:171] op_sel_hi:[1,0,0]
	v_pk_fma_f32 v[120:121], v[120:121], v[242:243], v[170:171] op_sel:[0,0,1] op_sel_hi:[1,0,1]
	v_pk_fma_f32 v[126:127], v[126:127], v[242:243], v[170:171] op_sel_hi:[1,0,0]
	v_pk_fma_f32 v[122:123], v[122:123], v[242:243], v[170:171] op_sel:[0,0,1] op_sel_hi:[1,0,1]
	v_pk_fma_f32 v[132:133], v[132:133], v[242:243], v[170:171] op_sel_hi:[1,0,0]
	v_pk_fma_f32 v[128:129], v[128:129], v[242:243], v[170:171] op_sel:[0,0,1] op_sel_hi:[1,0,1]
	v_pk_fma_f32 v[134:135], v[134:135], v[242:243], v[170:171] op_sel_hi:[1,0,0]
	v_pk_fma_f32 v[130:131], v[130:131], v[242:243], v[170:171] op_sel:[0,0,1] op_sel_hi:[1,0,1]
	v_min_f32_e32 v124, v243, v124
	v_min_f32_e32 v125, v243, v125
	v_min_f32_e32 v120, v243, v120
	v_min_f32_e32 v121, v243, v121
	v_min_f32_e32 v126, v243, v126
	v_min_f32_e32 v127, v243, v127
	v_min_f32_e32 v122, v243, v122
	v_min_f32_e32 v123, v243, v123
	v_min_f32_e32 v132, v243, v132
	v_min_f32_e32 v133, v243, v133
	v_min_f32_e32 v128, v243, v128
	v_min_f32_e32 v129, v243, v129
	v_min_f32_e32 v134, v243, v134
	v_min_f32_e32 v135, v243, v135
	v_min_f32_e32 v130, v243, v130
	v_min_f32_e32 v131, v243, v131
	v_exp_f32_e32 v124, v124
	v_exp_f32_e32 v125, v125
	v_exp_f32_e32 v120, v120
	v_exp_f32_e32 v121, v121
	v_exp_f32_e32 v126, v126
	v_exp_f32_e32 v127, v127
	v_exp_f32_e32 v122, v122
	v_exp_f32_e32 v123, v123
	v_exp_f32_e32 v132, v132
	v_exp_f32_e32 v133, v133
	v_exp_f32_e32 v128, v128
	v_exp_f32_e32 v129, v129
	v_exp_f32_e32 v134, v134
	v_exp_f32_e32 v135, v135
; #define LAS __attribute__((address_space(3)))
; DI unsigned pk2(float a, float b) { f32x2 v = {a, b}; bf2_t r = __builtin_convertvector(v, bf2_t); return __builtin_bit_cast(unsigned, r); }
; DI void phase_rglru(const Params& p, unsigned char* shm) {
;     ...
;                             const float ea = 1.f + __expf(fminf(-(acc[mt][0][j] + ba), 40.f)), ex = 1.f + __expf(fminf(-(acc[mt][1][j] + bx), 40.f));
;                             const float inv = __builtin_amdgcn_rcpf(ea * ex);
;                             const float r = inv * ex, ig = inv * ea;
;                             const float av = __expf(r * sp), om = 1.f - av;
;                             const float xcv = __uint_as_float((unsigned)*(const LAS bf16_t*)(lds + XC + t * TR + ch * 2) << 16);
;                             const float bt = __builtin_amdgcn_sqrtf(fmaxf(om * (1.f + av), 0.f)) * (ig * xcv);
;                             *(LAS bf16_t*)(lds + LAo + t * TR + ch * 2) = (bf16_t)(pk2(om, 0.f) & 0xffffu);
;                             *(LAS bf16_t*)(lds + BTo + t * TR + ch * 2) = (bf16_t)(pk2(bt, 0.f) & 0xffffu);
;                         }
	v_exp_f32_e32 v130, v130
	v_exp_f32_e32 v131, v131
	v_pk_add_f32 v[124:125], v[124:125], 1.0 op_sel_hi:[1,0]
	v_pk_add_f32 v[120:121], v[120:121], 1.0 op_sel_hi:[1,0]
	v_pk_add_f32 v[126:127], v[126:127], 1.0 op_sel_hi:[1,0]
	v_pk_add_f32 v[122:123], v[122:123], 1.0 op_sel_hi:[1,0]
	v_pk_add_f32 v[132:133], v[132:133], 1.0 op_sel_hi:[1,0]
	v_pk_add_f32 v[128:129], v[128:129], 1.0 op_sel_hi:[1,0]
	v_pk_add_f32 v[134:135], v[134:135], 1.0 op_sel_hi:[1,0]
	v_pk_add_f32 v[130:131], v[130:131], 1.0 op_sel_hi:[1,0]
	v_pk_mul_f32 v[210:211], v[124:125], v[120:121]
	v_pk_mul_f32 v[212:213], v[126:127], v[122:123]
	v_pk_mul_f32 v[214:215], v[132:133], v[128:129]
	v_pk_mul_f32 v[216:217], v[134:135], v[130:131]
	v_rcp_f32_e32 v210, v210
	v_rcp_f32_e32 v211, v211
	v_rcp_f32_e32 v212, v212
	v_rcp_f32_e32 v213, v213
	v_rcp_f32_e32 v214, v214
	v_rcp_f32_e32 v215, v215
	v_rcp_f32_e32 v216, v216
	v_rcp_f32_e32 v217, v217
	v_pk_mul_f32 v[120:121], v[120:121], v[210:211]
	v_pk_mul_f32 v[124:125], v[124:125], v[210:211]
	v_pk_mul_f32 v[122:123], v[122:123], v[212:213]
	v_pk_mul_f32 v[126:127], v[126:127], v[212:213]
	v_pk_mul_f32 v[128:129], v[128:129], v[214:215]
	v_pk_mul_f32 v[132:133], v[132:133], v[214:215]
	v_pk_mul_f32 v[130:131], v[130:131], v[216:217]
	v_pk_mul_f32 v[134:135], v[134:135], v[216:217]
	v_pk_mul_f32 v[120:121], v[120:121], v[204:205] op_sel:[0,1] op_sel_hi:[1,1]
	v_pk_mul_f32 v[122:123], v[122:123], v[204:205] op_sel:[0,1] op_sel_hi:[1,1]
	v_pk_mul_f32 v[128:129], v[128:129], v[204:205] op_sel:[0,1] op_sel_hi:[1,1]
	v_pk_mul_f32 v[130:131], v[130:131], v[204:205] op_sel:[0,1] op_sel_hi:[1,1]
	v_exp_f32_e32 v120, v120
	v_exp_f32_e32 v121, v121
	v_exp_f32_e32 v122, v122
	v_exp_f32_e32 v123, v123
	v_exp_f32_e32 v128, v128
	v_exp_f32_e32 v129, v129
	v_exp_f32_e32 v130, v130
	v_exp_f32_e32 v131, v131
	v_pk_add_f32 v[210:211], v[120:121], 1.0 op_sel_hi:[1,0] neg_lo:[1,0] neg_hi:[1,0]
	v_pk_add_f32 v[120:121], v[120:121], 1.0 op_sel_hi:[1,0]
	v_pk_add_f32 v[212:213], v[122:123], 1.0 op_sel_hi:[1,0] neg_lo:[1,0] neg_hi:[1,0]
	v_pk_add_f32 v[122:123], v[122:123], 1.0 op_sel_hi:[1,0]
	v_pk_add_f32 v[214:215], v[128:129], 1.0 op_sel_hi:[1,0] neg_lo:[1,0] neg_hi:[1,0]
	v_pk_add_f32 v[128:129], v[128:129], 1.0 op_sel_hi:[1,0]
	v_pk_add_f32 v[216:217], v[130:131], 1.0 op_sel_hi:[1,0] neg_lo:[1,0] neg_hi:[1,0]
	v_pk_add_f32 v[130:131], v[130:131], 1.0 op_sel_hi:[1,0]
	v_pk_mul_f32 v[120:121], v[210:211], v[120:121]
	v_pk_mul_f32 v[122:123], v[212:213], v[122:123]
	v_pk_mul_f32 v[128:129], v[214:215], v[128:129]
	v_pk_mul_f32 v[130:131], v[216:217], v[130:131]
	v_max_f32_e32 v120, 0, v120
	v_max_f32_e32 v121, 0, v121
	v_max_f32_e32 v122, 0, v122
	v_max_f32_e32 v123, 0, v123
	v_max_f32_e32 v128, 0, v128
	v_max_f32_e32 v129, 0, v129
	v_max_f32_e32 v130, 0, v130
	v_max_f32_e32 v131, 0, v131
	v_sqrt_f32_e32 v120, v120
	v_sqrt_f32_e32 v121, v121
	v_sqrt_f32_e32 v122, v122
	v_sqrt_f32_e32 v123, v123
	v_sqrt_f32_e32 v128, v128
	v_sqrt_f32_e32 v129, v129
	v_sqrt_f32_e32 v130, v130
	v_sqrt_f32_e32 v131, v131
	v_lshlrev_b32_e32 v234, 16, v234
	v_lshlrev_b32_e32 v235, 16, v235
	v_lshlrev_b32_e32 v236, 16, v236
	v_lshlrev_b32_e32 v237, 16, v237
	v_lshlrev_b32_e32 v238, 16, v238
	v_lshlrev_b32_e32 v239, 16, v239
	v_lshlrev_b32_e32 v240, 16, v240
	v_lshlrev_b32_e32 v241, 16, v241
	v_pk_mul_f32 v[124:125], v[124:125], v[234:235]
	v_pk_mul_f32 v[126:127], v[126:127], v[236:237]
	v_pk_mul_f32 v[132:133], v[132:133], v[238:239]
	v_pk_mul_f32 v[134:135], v[134:135], v[240:241]
	v_pk_mul_f32 v[124:125], v[124:125], v[120:121]
	v_pk_mul_f32 v[126:127], v[126:127], v[122:123]
	v_pk_mul_f32 v[132:133], v[132:133], v[128:129]
	v_pk_mul_f32 v[134:135], v[134:135], v[130:131]
	v_cvt_pk_bf16_f32 v210, v210, v211
	v_cvt_pk_bf16_f32 v124, v124, v125
	v_cvt_pk_bf16_f32 v212, v212, v213
	v_cvt_pk_bf16_f32 v126, v126, v127
	v_cvt_pk_bf16_f32 v214, v214, v215
	v_cvt_pk_bf16_f32 v132, v132, v133
	v_cvt_pk_bf16_f32 v216, v216, v217
	v_cvt_pk_bf16_f32 v134, v134, v135
	ds_write_b16 v195, v210 offset:12800
	ds_write_b16_d16_hi v195, v210 offset:13200
	ds_write_b16 v196, v124 offset:12800
	ds_write_b16_d16_hi v196, v124 offset:13200
	ds_write_b16 v195, v212 offset:13600
	ds_write_b16_d16_hi v195, v212 offset:14000
	ds_write_b16 v196, v126 offset:13600
	ds_write_b16_d16_hi v196, v126 offset:14000
	ds_write_b16 v195, v214 offset:19200
	ds_write_b16_d16_hi v195, v214 offset:19600
	ds_write_b16 v196, v132 offset:19200
	ds_write_b16_d16_hi v196, v132 offset:19600
	ds_write_b16 v195, v216 offset:20000
	ds_write_b16_d16_hi v195, v216 offset:20400
	ds_write_b16 v196, v134 offset:20000
	ds_write_b16_d16_hi v196, v134 offset:20400
	s_andn2_b64 vcc, exec, s[12:13]
	s_cbranch_vccnz .Lgates_b
; #define LAS __attribute__((address_space(3)))
; DI void phase_rglru(const Params& p, unsigned char* shm) {
;     ...
;                 for (int u = 0; u < 2; ++u) {
;                     if (u == 1 && w >= 4) break;
;                     f32x4 acc[4][2];
; #pragma unroll
;                     for (int mt = 0; mt < 4; ++mt) { acc[mt][0] = (f32x4){0.f, 0.f, 0.f, 0.f}; acc[mt][1] = (f32x4){0.f, 0.f, 0.f, 0.f}; }
; #pragma unroll
;                     for (int kk = 0; kk < 6; ++kk)
; #pragma unroll
;                         for (int mt = 0; mt < 4; ++mt) {
;                             const bf16x8 af = *(const LAS bf16x8*)(lds + XC + (16 * mt + fr) * TR + (32 * kk + 8 * fq) * 2);
;                             acc[mt][0] = __builtin_amdgcn_mfma_f32_16x16x32_bf16(af, Bf[u][kk], acc[mt][0], 0, 0, 0);
;                             acc[mt][1] = __builtin_amdgcn_mfma_f32_16x16x32_bf16(af, Bf[2 + u][kk], acc[mt][1], 0, 0, 0);
;                         }
;                     const int ch = chb + 16 * u + fr;
;                     const float ba = gb[ch], bx = gb[192 + ch], sp = gb[384 + ch];
; #pragma unroll
;                     for (int mt = 0; mt < 4; ++mt)
; #pragma unroll
;                         for (int j = 0; j < 4; ++j) {
;                             const int t = 16 * mt + 4 * fq + j;
;                             const float ea = 1.f + __expf(fminf(-(acc[mt][0][j] + ba), 40.f)), ex = 1.f + __expf(fminf(-(acc[mt][1][j] + bx), 40.f));
;                             const float inv = __builtin_amdgcn_rcpf(ea * ex);
;                             const float r = inv * ex, ig = inv * ea;
;                             const float av = __expf(r * sp), om = 1.f - av;
;                             const float xcv = __uint_as_float((unsigned)*(const LAS bf16_t*)(lds + XC + t * TR + ch * 2) << 16);
;                             const float bt = __builtin_amdgcn_sqrtf(fmaxf(om * (1.f + av), 0.f)) * (ig * xcv);
	ds_read_b128 v[120:123], v204 offset:26880
	ds_read_b128 v[124:127], v204 offset:33280
	ds_read_b128 v[128:131], v204 offset:26944
	ds_read_b128 v[132:135], v204 offset:33344
	ds_read_b128 v[226:229], v204 offset:27008
	s_waitcnt lgkmcnt(4)
	v_mfma_f32_16x16x32_bf16 v[148:151], v[120:123], v[24:27], 0
	v_mfma_f32_16x16x32_bf16 v[144:147], v[120:123], v[72:75], 0
	ds_read_b128 v[230:233], v204 offset:33408
	s_waitcnt lgkmcnt(4)
	v_mfma_f32_16x16x32_bf16 v[140:143], v[124:127], v[24:27], 0
	v_mfma_f32_16x16x32_bf16 v[136:139], v[124:127], v[72:75], 0
	ds_read_b128 v[120:123], v204 offset:27072
	s_waitcnt lgkmcnt(4)
	v_mfma_f32_16x16x32_bf16 v[148:151], v[128:131], v[28:31], v[148:151]
	v_mfma_f32_16x16x32_bf16 v[144:147], v[128:131], v[76:79], v[144:147]
	ds_read_b128 v[124:127], v204 offset:33472
	s_waitcnt lgkmcnt(4)
	v_mfma_f32_16x16x32_bf16 v[140:143], v[132:135], v[28:31], v[140:143]
	v_mfma_f32_16x16x32_bf16 v[136:139], v[132:135], v[76:79], v[136:139]
	ds_read_b128 v[128:131], v204 offset:27136
	s_waitcnt lgkmcnt(4)
	v_mfma_f32_16x16x32_bf16 v[148:151], v[226:229], v[32:35], v[148:151]
	v_mfma_f32_16x16x32_bf16 v[144:147], v[226:229], v[80:83], v[144:147]
	ds_read_b128 v[132:135], v204 offset:33536
	s_waitcnt lgkmcnt(4)
	v_mfma_f32_16x16x32_bf16 v[140:143], v[230:233], v[32:35], v[140:143]
	v_mfma_f32_16x16x32_bf16 v[136:139], v[230:233], v[80:83], v[136:139]
	ds_read_b128 v[226:229], v204 offset:27200
	s_waitcnt lgkmcnt(4)
	v_mfma_f32_16x16x32_bf16 v[148:151], v[120:123], v[36:39], v[148:151]
	v_mfma_f32_16x16x32_bf16 v[144:147], v[120:123], v[84:87], v[144:147]
	ds_read_b128 v[230:233], v204 offset:33600
	s_waitcnt lgkmcnt(4)
	v_mfma_f32_16x16x32_bf16 v[140:143], v[124:127], v[36:39], v[140:143]
	v_mfma_f32_16x16x32_bf16 v[136:139], v[124:127], v[84:87], v[136:139]
	s_waitcnt lgkmcnt(3)
	v_mfma_f32_16x16x32_bf16 v[148:151], v[128:131], v[40:43], v[148:151]
	v_mfma_f32_16x16x32_bf16 v[144:147], v[128:131], v[88:91], v[144:147]
	s_waitcnt lgkmcnt(2)
	v_mfma_f32_16x16x32_bf16 v[140:143], v[132:135], v[40:43], v[140:143]
	v_mfma_f32_16x16x32_bf16 v[136:139], v[132:135], v[88:91], v[136:139]
	s_waitcnt lgkmcnt(1)
	v_mfma_f32_16x16x32_bf16 v[148:151], v[226:229], v[44:47], v[148:151]
	v_mfma_f32_16x16x32_bf16 v[144:147], v[226:229], v[92:95], v[144:147]
	s_waitcnt lgkmcnt(0)
	v_mfma_f32_16x16x32_bf16 v[140:143], v[230:233], v[44:47], v[140:143]
	v_mfma_f32_16x16x32_bf16 v[136:139], v[230:233], v[92:95], v[136:139]
	s_nop 1
	ds_read2st64_b32 v[170:171], v185 offset1:3
	ds_read_b32 v205, v185 offset:1536
	ds_read_u16 v226, v197 offset:26880
	ds_read_u16 v227, v197 offset:27280
	ds_read_u16 v228, v197 offset:27680
	ds_read_u16 v229, v197 offset:28080
	ds_read_u16 v230, v197 offset:33280
	ds_read_u16 v231, v197 offset:33680
	ds_read_u16 v232, v197 offset:34080
	ds_read_u16 v233, v197 offset:34480
	ds_read_u16 v234, v197 offset:39680
	ds_read_u16 v235, v197 offset:40080
	ds_read_u16 v236, v197 offset:40480
	ds_read_u16 v237, v197 offset:40880
	ds_read_u16 v238, v197 offset:46080
	ds_read_u16 v239, v197 offset:46480
	ds_read_u16 v240, v197 offset:46880
	ds_read_u16 v241, v197 offset:47280
	s_waitcnt lgkmcnt(15)
	v_mov_b32_e32 v242, 0xbfb8aa3b
	v_mov_b32_e32 v243, 0x4266d4ca
	v_mul_f32_e32 v170, v242, v170
	v_mul_f32_e32 v171, v242, v171
	v_mul_f32_e32 v205, 0x3fb8aa3b, v205
	v_pk_fma_f32 v[148:149], v[148:149], v[242:243], v[170:171] op_sel_hi:[1,0,0]
	v_pk_fma_f32 v[144:145], v[144:145], v[242:243], v[170:171] op_sel:[0,0,1] op_sel_hi:[1,0,1]
	v_pk_fma_f32 v[150:151], v[150:151], v[242:243], v[170:171] op_sel_hi:[1,0,0]
	v_pk_fma_f32 v[146:147], v[146:147], v[242:243], v[170:171] op_sel:[0,0,1] op_sel_hi:[1,0,1]
	v_pk_fma_f32 v[140:141], v[140:141], v[242:243], v[170:171] op_sel_hi:[1,0,0]
	v_pk_fma_f32 v[136:137], v[136:137], v[242:243], v[170:171] op_sel:[0,0,1] op_sel_hi:[1,0,1]
	v_pk_fma_f32 v[142:143], v[142:143], v[242:243], v[170:171] op_sel_hi:[1,0,0]
	v_pk_fma_f32 v[138:139], v[138:139], v[242:243], v[170:171] op_sel:[0,0,1] op_sel_hi:[1,0,1]
	v_min_f32_e32 v148, v243, v148
	v_min_f32_e32 v149, v243, v149
	v_min_f32_e32 v144, v243, v144
	v_min_f32_e32 v145, v243, v145
	v_min_f32_e32 v150, v243, v150
	v_min_f32_e32 v151, v243, v151
	v_min_f32_e32 v146, v243, v146
	v_min_f32_e32 v147, v243, v147
	v_min_f32_e32 v140, v243, v140
	v_min_f32_e32 v141, v243, v141
	v_min_f32_e32 v136, v243, v136
	v_min_f32_e32 v137, v243, v137
	v_min_f32_e32 v142, v243, v142
	v_min_f32_e32 v143, v243, v143
	v_min_f32_e32 v138, v243, v138
	v_min_f32_e32 v139, v243, v139
	v_exp_f32_e32 v148, v148
	v_exp_f32_e32 v149, v149
	v_exp_f32_e32 v144, v144
	v_exp_f32_e32 v145, v145
	v_exp_f32_e32 v150, v150
	v_exp_f32_e32 v151, v151
	v_exp_f32_e32 v146, v146
	v_exp_f32_e32 v147, v147
	v_exp_f32_e32 v140, v140
	v_exp_f32_e32 v141, v141
	v_exp_f32_e32 v136, v136
	v_exp_f32_e32 v137, v137
	v_exp_f32_e32 v142, v142
	v_exp_f32_e32 v143, v143
	v_exp_f32_e32 v138, v138
	v_exp_f32_e32 v139, v139
	v_pk_add_f32 v[148:149], v[148:149], 1.0 op_sel_hi:[1,0]
	v_pk_add_f32 v[144:145], v[144:145], 1.0 op_sel_hi:[1,0]
	v_pk_add_f32 v[150:151], v[150:151], 1.0 op_sel_hi:[1,0]
	v_pk_add_f32 v[146:147], v[146:147], 1.0 op_sel_hi:[1,0]
	v_pk_add_f32 v[140:141], v[140:141], 1.0 op_sel_hi:[1,0]
	v_pk_add_f32 v[136:137], v[136:137], 1.0 op_sel_hi:[1,0]
	v_pk_add_f32 v[142:143], v[142:143], 1.0 op_sel_hi:[1,0]
	v_pk_add_f32 v[138:139], v[138:139], 1.0 op_sel_hi:[1,0]
	v_pk_mul_f32 v[210:211], v[148:149], v[144:145]
	v_pk_mul_f32 v[212:213], v[150:151], v[146:147]
	v_pk_mul_f32 v[214:215], v[140:141], v[136:137]
	v_pk_mul_f32 v[216:217], v[142:143], v[138:139]
	v_rcp_f32_e32 v210, v210
; #define LAS __attribute__((address_space(3)))
; DI unsigned pk2(float a, float b) { f32x2 v = {a, b}; bf2_t r = __builtin_convertvector(v, bf2_t); return __builtin_bit_cast(unsigned, r); }
; DI void phase_rglru(const Params& p, unsigned char* shm) {
;     ...
;                 for (int u = 0; u < 2; ++u) {
;                     if (u == 1 && w >= 4) break;
;                     f32x4 acc[4][2];
; #pragma unroll
;                     for (int mt = 0; mt < 4; ++mt) { acc[mt][0] = (f32x4){0.f, 0.f, 0.f, 0.f}; acc[mt][1] = (f32x4){0.f, 0.f, 0.f, 0.f}; }
; #pragma unroll
;                     for (int kk = 0; kk < 6; ++kk)
; #pragma unroll
;                         for (int mt = 0; mt < 4; ++mt) {
;                             const bf16x8 af = *(const LAS bf16x8*)(lds + XC + (16 * mt + fr) * TR + (32 * kk + 8 * fq) * 2);
;                             acc[mt][0] = __builtin_amdgcn_mfma_f32_16x16x32_bf16(af, Bf[u][kk], acc[mt][0], 0, 0, 0);
;                             acc[mt][1] = __builtin_amdgcn_mfma_f32_16x16x32_bf16(af, Bf[2 + u][kk], acc[mt][1], 0, 0, 0);
;                         }
;     ...
;                             const float ea = 1.f + __expf(fminf(-(acc[mt][0][j] + ba), 40.f)), ex = 1.f + __expf(fminf(-(acc[mt][1][j] + bx), 40.f));
;                             const float inv = __builtin_amdgcn_rcpf(ea * ex);
;                             const float r = inv * ex, ig = inv * ea;
;                             const float av = __expf(r * sp), om = 1.f - av;
;                             const float xcv = __uint_as_float((unsigned)*(const LAS bf16_t*)(lds + XC + t * TR + ch * 2) << 16);
;                             const float bt = __builtin_amdgcn_sqrtf(fmaxf(om * (1.f + av), 0.f)) * (ig * xcv);
;                             *(LAS bf16_t*)(lds + LAo + t * TR + ch * 2) = (bf16_t)(pk2(om, 0.f) & 0xffffu);
;                             *(LAS bf16_t*)(lds + BTo + t * TR + ch * 2) = (bf16_t)(pk2(bt, 0.f) & 0xffffu);
	v_rcp_f32_e32 v211, v211
	v_rcp_f32_e32 v212, v212
	v_rcp_f32_e32 v213, v213
	v_rcp_f32_e32 v214, v214
	v_rcp_f32_e32 v215, v215
	v_rcp_f32_e32 v216, v216
	v_rcp_f32_e32 v217, v217
	v_pk_mul_f32 v[144:145], v[144:145], v[210:211]
	v_pk_mul_f32 v[148:149], v[148:149], v[210:211]
	v_pk_mul_f32 v[146:147], v[146:147], v[212:213]
	v_pk_mul_f32 v[150:151], v[150:151], v[212:213]
	v_pk_mul_f32 v[136:137], v[136:137], v[214:215]
	v_pk_mul_f32 v[140:141], v[140:141], v[214:215]
	v_pk_mul_f32 v[138:139], v[138:139], v[216:217]
	v_pk_mul_f32 v[142:143], v[142:143], v[216:217]
	v_pk_mul_f32 v[144:145], v[144:145], v[204:205] op_sel:[0,1] op_sel_hi:[1,1]
	v_pk_mul_f32 v[146:147], v[146:147], v[204:205] op_sel:[0,1] op_sel_hi:[1,1]
	v_pk_mul_f32 v[136:137], v[136:137], v[204:205] op_sel:[0,1] op_sel_hi:[1,1]
	v_pk_mul_f32 v[138:139], v[138:139], v[204:205] op_sel:[0,1] op_sel_hi:[1,1]
	v_exp_f32_e32 v144, v144
	v_exp_f32_e32 v145, v145
	v_exp_f32_e32 v146, v146
	v_exp_f32_e32 v147, v147
	v_exp_f32_e32 v136, v136
	v_exp_f32_e32 v137, v137
	v_exp_f32_e32 v138, v138
	v_exp_f32_e32 v139, v139
	v_pk_add_f32 v[210:211], v[144:145], 1.0 op_sel_hi:[1,0] neg_lo:[1,0] neg_hi:[1,0]
	v_pk_add_f32 v[144:145], v[144:145], 1.0 op_sel_hi:[1,0]
	v_pk_add_f32 v[212:213], v[146:147], 1.0 op_sel_hi:[1,0] neg_lo:[1,0] neg_hi:[1,0]
	v_pk_add_f32 v[146:147], v[146:147], 1.0 op_sel_hi:[1,0]
	v_pk_add_f32 v[214:215], v[136:137], 1.0 op_sel_hi:[1,0] neg_lo:[1,0] neg_hi:[1,0]
	v_pk_add_f32 v[136:137], v[136:137], 1.0 op_sel_hi:[1,0]
	v_pk_add_f32 v[216:217], v[138:139], 1.0 op_sel_hi:[1,0] neg_lo:[1,0] neg_hi:[1,0]
	v_pk_add_f32 v[138:139], v[138:139], 1.0 op_sel_hi:[1,0]
	v_pk_mul_f32 v[144:145], v[210:211], v[144:145]
	v_pk_mul_f32 v[146:147], v[212:213], v[146:147]
	v_pk_mul_f32 v[136:137], v[214:215], v[136:137]
	v_pk_mul_f32 v[138:139], v[216:217], v[138:139]
	v_max_f32_e32 v144, 0, v144
	v_max_f32_e32 v145, 0, v145
	v_max_f32_e32 v146, 0, v146
	v_max_f32_e32 v147, 0, v147
	v_max_f32_e32 v136, 0, v136
	v_max_f32_e32 v137, 0, v137
	v_max_f32_e32 v138, 0, v138
	v_max_f32_e32 v139, 0, v139
	v_sqrt_f32_e32 v144, v144
	v_sqrt_f32_e32 v145, v145
	v_sqrt_f32_e32 v146, v146
	v_sqrt_f32_e32 v147, v147
	v_sqrt_f32_e32 v136, v136
	v_sqrt_f32_e32 v137, v137
	v_sqrt_f32_e32 v138, v138
	v_sqrt_f32_e32 v139, v139
	s_waitcnt lgkmcnt(0)
	v_lshlrev_b32_e32 v226, 16, v226
	v_lshlrev_b32_e32 v227, 16, v227
	v_lshlrev_b32_e32 v228, 16, v228
	v_lshlrev_b32_e32 v229, 16, v229
	v_lshlrev_b32_e32 v230, 16, v230
	v_lshlrev_b32_e32 v231, 16, v231
	v_lshlrev_b32_e32 v232, 16, v232
	v_lshlrev_b32_e32 v233, 16, v233
	v_pk_mul_f32 v[148:149], v[148:149], v[226:227]
	v_pk_mul_f32 v[150:151], v[150:151], v[228:229]
	v_pk_mul_f32 v[140:141], v[140:141], v[230:231]
	v_pk_mul_f32 v[142:143], v[142:143], v[232:233]
	v_pk_mul_f32 v[148:149], v[148:149], v[144:145]
	v_pk_mul_f32 v[150:151], v[150:151], v[146:147]
	v_pk_mul_f32 v[140:141], v[140:141], v[136:137]
	v_pk_mul_f32 v[142:143], v[142:143], v[138:139]
	v_cvt_pk_bf16_f32 v210, v210, v211
	v_cvt_pk_bf16_f32 v148, v148, v149
	v_cvt_pk_bf16_f32 v212, v212, v213
	v_cvt_pk_bf16_f32 v150, v150, v151
	v_cvt_pk_bf16_f32 v214, v214, v215
	v_cvt_pk_bf16_f32 v140, v140, v141
	v_cvt_pk_bf16_f32 v216, v216, v217
	v_cvt_pk_bf16_f32 v142, v142, v143
	ds_write_b16 v198, v210
	ds_write_b16_d16_hi v198, v210 offset:400
	ds_write_b16 v199, v148
	ds_write_b16_d16_hi v199, v148 offset:400
	ds_write_b16 v198, v212 offset:800
	ds_write_b16_d16_hi v198, v212 offset:1200
	ds_write_b16 v199, v150 offset:800
	ds_write_b16_d16_hi v199, v150 offset:1200
	ds_write_b16 v198, v214 offset:6400
	ds_write_b16_d16_hi v198, v214 offset:6800
	ds_write_b16 v199, v140 offset:6400
	ds_write_b16_d16_hi v199, v140 offset:6800
	ds_write_b16 v198, v216 offset:7200
	ds_write_b16_d16_hi v198, v216 offset:7600
	ds_write_b16 v199, v142 offset:7200
	ds_write_b16_d16_hi v199, v142 offset:7600
	s_branch .LBB0_847
.Lgates_b:
	ds_read_b128 v[120:123], v204 offset:39680
	ds_read_b128 v[124:127], v204 offset:46080
	ds_read_b128 v[128:131], v204 offset:39744
	ds_read_b128 v[132:135], v204 offset:46144
	ds_read_b128 v[226:229], v204 offset:39808
	s_waitcnt lgkmcnt(4)
	v_mfma_f32_16x16x32_bf16 v[214:217], v[120:123], v[24:27], 0
	v_mfma_f32_16x16x32_bf16 v[210:213], v[120:123], v[72:75], 0
	ds_read_b128 v[230:233], v204 offset:46208
	s_waitcnt lgkmcnt(4)
	v_mfma_f32_16x16x32_bf16 v[218:221], v[124:127], v[24:27], 0
	v_mfma_f32_16x16x32_bf16 v[222:225], v[124:127], v[72:75], 0
	ds_read_b128 v[120:123], v204 offset:39872
	s_waitcnt lgkmcnt(4)
	v_mfma_f32_16x16x32_bf16 v[214:217], v[128:131], v[28:31], v[214:217]
	v_mfma_f32_16x16x32_bf16 v[210:213], v[128:131], v[76:79], v[210:213]
	ds_read_b128 v[124:127], v204 offset:46272
	s_waitcnt lgkmcnt(4)
	v_mfma_f32_16x16x32_bf16 v[218:221], v[132:135], v[28:31], v[218:221]
	v_mfma_f32_16x16x32_bf16 v[222:225], v[132:135], v[76:79], v[222:225]
	ds_read_b128 v[128:131], v204 offset:39936
	s_waitcnt lgkmcnt(4)
	v_mfma_f32_16x16x32_bf16 v[214:217], v[226:229], v[32:35], v[214:217]
	v_mfma_f32_16x16x32_bf16 v[210:213], v[226:229], v[80:83], v[210:213]
	ds_read_b128 v[132:135], v204 offset:46336
	s_waitcnt lgkmcnt(4)
	v_mfma_f32_16x16x32_bf16 v[218:221], v[230:233], v[32:35], v[218:221]
	v_mfma_f32_16x16x32_bf16 v[222:225], v[230:233], v[80:83], v[222:225]
	s_waitcnt lgkmcnt(3)
	v_mfma_f32_16x16x32_bf16 v[214:217], v[120:123], v[36:39], v[214:217]
	v_mfma_f32_16x16x32_bf16 v[210:213], v[120:123], v[84:87], v[210:213]
	s_waitcnt lgkmcnt(2)
	v_mfma_f32_16x16x32_bf16 v[218:221], v[124:127], v[36:39], v[218:221]
	v_mfma_f32_16x16x32_bf16 v[222:225], v[124:127], v[84:87], v[222:225]
	s_waitcnt lgkmcnt(1)
; #define LAS __attribute__((address_space(3)))
; DI void phase_rglru(const Params& p, unsigned char* shm) {
;     ...
;                     for (int kk = 0; kk < 6; ++kk)
; #pragma unroll
;                         for (int mt = 0; mt < 4; ++mt) {
;                             const bf16x8 af = *(const LAS bf16x8*)(lds + XC + (16 * mt + fr) * TR + (32 * kk + 8 * fq) * 2);
;                             acc[mt][0] = __builtin_amdgcn_mfma_f32_16x16x32_bf16(af, Bf[u][kk], acc[mt][0], 0, 0, 0);
;                             acc[mt][1] = __builtin_amdgcn_mfma_f32_16x16x32_bf16(af, Bf[2 + u][kk], acc[mt][1], 0, 0, 0);
;                         }
;                     const int ch = chb + 16 * u + fr;
;                     const float ba = gb[ch], bx = gb[192 + ch], sp = gb[384 + ch];
; #pragma unroll
;                     for (int mt = 0; mt < 4; ++mt)
; #pragma unroll
;                         for (int j = 0; j < 4; ++j) {
;                             const int t = 16 * mt + 4 * fq + j;
;                             const float ea = 1.f + __expf(fminf(-(acc[mt][0][j] + ba), 40.f)), ex = 1.f + __expf(fminf(-(acc[mt][1][j] + bx), 40.f));
;                             const float inv = __builtin_amdgcn_rcpf(ea * ex);
;                             const float r = inv * ex, ig = inv * ea;
;                             const float av = __expf(r * sp), om = 1.f - av;
;                             const float xcv = __uint_as_float((unsigned)*(const LAS bf16_t*)(lds + XC + t * TR + ch * 2) << 16);
;                             const float bt = __builtin_amdgcn_sqrtf(fmaxf(om * (1.f + av), 0.f)) * (ig * xcv);
	v_mfma_f32_16x16x32_bf16 v[214:217], v[128:131], v[40:43], v[214:217]
	v_mfma_f32_16x16x32_bf16 v[210:213], v[128:131], v[88:91], v[210:213]
	s_waitcnt lgkmcnt(0)
	v_mfma_f32_16x16x32_bf16 v[218:221], v[132:135], v[40:43], v[218:221]
	v_mfma_f32_16x16x32_bf16 v[222:225], v[132:135], v[88:91], v[222:225]
	ds_read_b128 v[120:123], v204 offset:40000
	s_nop 1
	ds_read_b128 v[128:131], v204 offset:46400
	ds_read2st64_b32 v[170:171], v185 offset1:3
	ds_read_b32 v205, v185 offset:1536
	ds_read_u16 v226, v197 offset:26880
	ds_read_u16 v227, v197 offset:27280
	ds_read_u16 v228, v197 offset:27680
	ds_read_u16 v229, v197 offset:28080
	ds_read_u16 v230, v197 offset:33280
	ds_read_u16 v231, v197 offset:33680
	ds_read_u16 v232, v197 offset:34080
	ds_read_u16 v233, v197 offset:34480
	ds_read_u16 v234, v197 offset:39680
	ds_read_u16 v235, v197 offset:40080
	ds_read_u16 v236, v197 offset:40480
	ds_read_u16 v237, v197 offset:40880
	ds_read_u16 v238, v197 offset:46080
	ds_read_u16 v239, v197 offset:46480
	ds_read_u16 v240, v197 offset:46880
	ds_read_u16 v241, v197 offset:47280
	s_waitcnt lgkmcnt(15)
	v_mov_b32_e32 v242, 0xbfb8aa3b
	v_mov_b32_e32 v243, 0x4266d4ca
	v_mul_f32_e32 v170, v242, v170
	v_mul_f32_e32 v171, v242, v171
	v_mul_f32_e32 v205, 0x3fb8aa3b, v205
	v_mfma_f32_16x16x32_bf16 v[124:127], v[120:123], v[44:47], v[214:217]
	v_mfma_f32_16x16x32_bf16 v[120:123], v[120:123], v[92:95], v[210:213]
	v_mfma_f32_16x16x32_bf16 v[132:135], v[128:131], v[44:47], v[218:221]
	v_mfma_f32_16x16x32_bf16 v[128:131], v[128:131], v[92:95], v[222:225]
	s_nop 8
	v_pk_fma_f32 v[124:125], v[124:125], v[242:243], v[170:171] op_sel_hi:[1,0,0]
	v_pk_fma_f32 v[120:121], v[120:121], v[242:243], v[170:171] op_sel:[0,0,1] op_sel_hi:[1,0,1]
	v_pk_fma_f32 v[126:127], v[126:127], v[242:243], v[170:171] op_sel_hi:[1,0,0]
	v_pk_fma_f32 v[122:123], v[122:123], v[242:243], v[170:171] op_sel:[0,0,1] op_sel_hi:[1,0,1]
	v_pk_fma_f32 v[132:133], v[132:133], v[242:243], v[170:171] op_sel_hi:[1,0,0]
	v_pk_fma_f32 v[128:129], v[128:129], v[242:243], v[170:171] op_sel:[0,0,1] op_sel_hi:[1,0,1]
	v_pk_fma_f32 v[134:135], v[134:135], v[242:243], v[170:171] op_sel_hi:[1,0,0]
	v_pk_fma_f32 v[130:131], v[130:131], v[242:243], v[170:171] op_sel:[0,0,1] op_sel_hi:[1,0,1]
	v_min_f32_e32 v124, v243, v124
	v_min_f32_e32 v125, v243, v125
	v_min_f32_e32 v120, v243, v120
	v_min_f32_e32 v121, v243, v121
	v_min_f32_e32 v126, v243, v126
	v_min_f32_e32 v127, v243, v127
	v_min_f32_e32 v122, v243, v122
	v_min_f32_e32 v123, v243, v123
	v_min_f32_e32 v132, v243, v132
	v_min_f32_e32 v133, v243, v133
	v_min_f32_e32 v128, v243, v128
	v_min_f32_e32 v129, v243, v129
	v_min_f32_e32 v134, v243, v134
	v_min_f32_e32 v135, v243, v135
	v_min_f32_e32 v130, v243, v130
	v_min_f32_e32 v131, v243, v131
	v_exp_f32_e32 v124, v124
	v_exp_f32_e32 v125, v125
	v_exp_f32_e32 v120, v120
	v_exp_f32_e32 v121, v121
	v_exp_f32_e32 v126, v126
	v_exp_f32_e32 v127, v127
	v_exp_f32_e32 v122, v122
	v_exp_f32_e32 v123, v123
	v_exp_f32_e32 v132, v132
	v_exp_f32_e32 v133, v133
	v_exp_f32_e32 v128, v128
	v_exp_f32_e32 v129, v129
	v_exp_f32_e32 v134, v134
	v_exp_f32_e32 v135, v135
	v_exp_f32_e32 v130, v130
	v_exp_f32_e32 v131, v131
	v_pk_add_f32 v[124:125], v[124:125], 1.0 op_sel_hi:[1,0]
	v_pk_add_f32 v[120:121], v[120:121], 1.0 op_sel_hi:[1,0]
	v_pk_add_f32 v[126:127], v[126:127], 1.0 op_sel_hi:[1,0]
	v_pk_add_f32 v[122:123], v[122:123], 1.0 op_sel_hi:[1,0]
	v_pk_add_f32 v[132:133], v[132:133], 1.0 op_sel_hi:[1,0]
	v_pk_add_f32 v[128:129], v[128:129], 1.0 op_sel_hi:[1,0]
	v_pk_add_f32 v[134:135], v[134:135], 1.0 op_sel_hi:[1,0]
	v_pk_add_f32 v[130:131], v[130:131], 1.0 op_sel_hi:[1,0]
	v_pk_mul_f32 v[210:211], v[124:125], v[120:121]
	v_pk_mul_f32 v[212:213], v[126:127], v[122:123]
	v_pk_mul_f32 v[214:215], v[132:133], v[128:129]
	v_pk_mul_f32 v[216:217], v[134:135], v[130:131]
	v_rcp_f32_e32 v210, v210
	v_rcp_f32_e32 v211, v211
	v_rcp_f32_e32 v212, v212
	v_rcp_f32_e32 v213, v213
	v_rcp_f32_e32 v214, v214
	v_rcp_f32_e32 v215, v215
	v_rcp_f32_e32 v216, v216
	v_rcp_f32_e32 v217, v217
	v_pk_mul_f32 v[120:121], v[120:121], v[210:211]
	v_pk_mul_f32 v[124:125], v[124:125], v[210:211]
	v_pk_mul_f32 v[122:123], v[122:123], v[212:213]
	v_pk_mul_f32 v[126:127], v[126:127], v[212:213]
	v_pk_mul_f32 v[128:129], v[128:129], v[214:215]
	v_pk_mul_f32 v[132:133], v[132:133], v[214:215]
	v_pk_mul_f32 v[130:131], v[130:131], v[216:217]
	v_pk_mul_f32 v[134:135], v[134:135], v[216:217]
	v_pk_mul_f32 v[120:121], v[120:121], v[204:205] op_sel:[0,1] op_sel_hi:[1,1]
	v_pk_mul_f32 v[122:123], v[122:123], v[204:205] op_sel:[0,1] op_sel_hi:[1,1]
	v_pk_mul_f32 v[128:129], v[128:129], v[204:205] op_sel:[0,1] op_sel_hi:[1,1]
	v_pk_mul_f32 v[130:131], v[130:131], v[204:205] op_sel:[0,1] op_sel_hi:[1,1]
	v_exp_f32_e32 v120, v120
	v_exp_f32_e32 v121, v121
	v_exp_f32_e32 v122, v122
	v_exp_f32_e32 v123, v123
	v_exp_f32_e32 v128, v128
	v_exp_f32_e32 v129, v129
	v_exp_f32_e32 v130, v130
	v_exp_f32_e32 v131, v131
	v_pk_add_f32 v[210:211], v[120:121], 1.0 op_sel_hi:[1,0] neg_lo:[1,0] neg_hi:[1,0]
	v_pk_add_f32 v[120:121], v[120:121], 1.0 op_sel_hi:[1,0]
	v_pk_add_f32 v[212:213], v[122:123], 1.0 op_sel_hi:[1,0] neg_lo:[1,0] neg_hi:[1,0]
	v_pk_add_f32 v[122:123], v[122:123], 1.0 op_sel_hi:[1,0]
	v_pk_add_f32 v[214:215], v[128:129], 1.0 op_sel_hi:[1,0] neg_lo:[1,0] neg_hi:[1,0]
	v_pk_add_f32 v[128:129], v[128:129], 1.0 op_sel_hi:[1,0]
	v_pk_add_f32 v[216:217], v[130:131], 1.0 op_sel_hi:[1,0] neg_lo:[1,0] neg_hi:[1,0]
	v_pk_add_f32 v[130:131], v[130:131], 1.0 op_sel_hi:[1,0]
	v_pk_mul_f32 v[120:121], v[210:211], v[120:121]
	v_pk_mul_f32 v[122:123], v[212:213], v[122:123]
	v_pk_mul_f32 v[128:129], v[214:215], v[128:129]
	v_pk_mul_f32 v[130:131], v[216:217], v[130:131]
	v_max_f32_e32 v120, 0, v120
	v_max_f32_e32 v121, 0, v121
	v_max_f32_e32 v122, 0, v122
	v_max_f32_e32 v123, 0, v123
	v_max_f32_e32 v128, 0, v128
	v_max_f32_e32 v129, 0, v129
	v_max_f32_e32 v130, 0, v130
	v_max_f32_e32 v131, 0, v131
	v_sqrt_f32_e32 v120, v120
	v_sqrt_f32_e32 v121, v121
	v_sqrt_f32_e32 v122, v122
	v_sqrt_f32_e32 v123, v123
	v_sqrt_f32_e32 v128, v128
	v_sqrt_f32_e32 v129, v129
	v_sqrt_f32_e32 v130, v130
	v_sqrt_f32_e32 v131, v131
	s_waitcnt lgkmcnt(0)
; #define LAS __attribute__((address_space(3)))
; DI unsigned pk2(float a, float b) { f32x2 v = {a, b}; bf2_t r = __builtin_convertvector(v, bf2_t); return __builtin_bit_cast(unsigned, r); }
; DI void phase_rglru(const Params& p, unsigned char* shm) {
;     ...
;                             const float xcv = __uint_as_float((unsigned)*(const LAS bf16_t*)(lds + XC + t * TR + ch * 2) << 16);
;                             const float bt = __builtin_amdgcn_sqrtf(fmaxf(om * (1.f + av), 0.f)) * (ig * xcv);
;                             *(LAS bf16_t*)(lds + LAo + t * TR + ch * 2) = (bf16_t)(pk2(om, 0.f) & 0xffffu);
;                             *(LAS bf16_t*)(lds + BTo + t * TR + ch * 2) = (bf16_t)(pk2(bt, 0.f) & 0xffffu);
	v_lshlrev_b32_e32 v234, 16, v234
	v_lshlrev_b32_e32 v235, 16, v235
	v_lshlrev_b32_e32 v236, 16, v236
	v_lshlrev_b32_e32 v237, 16, v237
	v_lshlrev_b32_e32 v238, 16, v238
	v_lshlrev_b32_e32 v239, 16, v239
	v_lshlrev_b32_e32 v240, 16, v240
	v_lshlrev_b32_e32 v241, 16, v241
	v_pk_mul_f32 v[124:125], v[124:125], v[234:235]
	v_pk_mul_f32 v[126:127], v[126:127], v[236:237]
	v_pk_mul_f32 v[132:133], v[132:133], v[238:239]
	v_pk_mul_f32 v[134:135], v[134:135], v[240:241]
	v_pk_mul_f32 v[124:125], v[124:125], v[120:121]
	v_pk_mul_f32 v[126:127], v[126:127], v[122:123]
	v_pk_mul_f32 v[132:133], v[132:133], v[128:129]
	v_pk_mul_f32 v[134:135], v[134:135], v[130:131]
	v_cvt_pk_bf16_f32 v210, v210, v211
	v_cvt_pk_bf16_f32 v124, v124, v125
	v_cvt_pk_bf16_f32 v212, v212, v213
	v_cvt_pk_bf16_f32 v126, v126, v127
	v_cvt_pk_bf16_f32 v214, v214, v215
	v_cvt_pk_bf16_f32 v132, v132, v133
	v_cvt_pk_bf16_f32 v216, v216, v217
	v_cvt_pk_bf16_f32 v134, v134, v135
	ds_write_b16 v198, v210 offset:12800
	ds_write_b16_d16_hi v198, v210 offset:13200
	ds_write_b16 v199, v124 offset:12800
	ds_write_b16_d16_hi v199, v124 offset:13200
	ds_write_b16 v198, v212 offset:13600
	ds_write_b16_d16_hi v198, v212 offset:14000
	ds_write_b16 v199, v126 offset:13600
	ds_write_b16_d16_hi v199, v126 offset:14000
	ds_write_b16 v198, v214 offset:19200
	ds_write_b16_d16_hi v198, v214 offset:19600
	ds_write_b16 v199, v132 offset:19200
	ds_write_b16_d16_hi v199, v132 offset:19600
	ds_write_b16 v198, v216 offset:20000
	ds_write_b16_d16_hi v198, v216 offset:20400
	ds_write_b16 v199, v134 offset:20000
	ds_write_b16_d16_hi v199, v134 offset:20400
